# v20 + ph_up act stores marked nt (streaming output, read next phase)
# speedup vs baseline: 1.0039x; 1.0039x over previous
.LBB0_42:
	ds_read2_b64 v[50:53], v62 offset1:32
	s_waitcnt lgkmcnt(2)
	v_lshlrev_b32_e32 v44, 16, v34
	v_and_b32_e32 v45, 0xffff0000, v34
	s_waitcnt lgkmcnt(1)
	v_lshlrev_b32_e32 v48, 16, v38
	v_and_b32_e32 v49, 0xffff0000, v38
	v_pk_fma_f32 v[44:45], v[2:3], v[44:45], v[26:27]
	s_waitcnt lgkmcnt(0)
	v_lshlrev_b32_e32 v46, 16, v50
	v_and_b32_e32 v47, 0xffff0000, v50
	v_pk_fma_f32 v[44:45], v[10:11], v[48:49], v[44:45]
	v_lshlrev_b32_e32 v58, 16, v36
	v_pk_fma_f32 v[44:45], v[18:19], v[46:47], v[44:45]
	v_and_b32_e32 v59, 0xffff0000, v36
	v_pk_mul_f32 v[54:55], v[44:45], v[44:45]
	v_lshlrev_b32_e32 v60, 16, v40
	v_fmamk_f32 v34, v54, 0xbdd2d3e8, v178
	v_mul_f32_e32 v34, v44, v34
	v_exp_f32_e32 v34, v34
	v_and_b32_e32 v61, 0xffff0000, v40
	v_pk_fma_f32 v[58:59], v[6:7], v[58:59], v[30:31]
	v_lshlrev_b32_e32 v56, 16, v52
	v_add_f32_e32 v34, 1.0, v34
	v_rcp_f32_e32 v54, v34
	v_fmamk_f32 v34, v55, 0xbdd2d3e8, v178
	v_mul_f32_e32 v34, v45, v34
	v_exp_f32_e32 v34, v34
	v_and_b32_e32 v57, 0xffff0000, v52
	v_pk_fma_f32 v[58:59], v[14:15], v[60:61], v[58:59]
	v_lshlrev_b32_e32 v38, 16, v51
	v_add_f32_e32 v34, 1.0, v34
	v_rcp_f32_e32 v55, v34
	v_pk_fma_f32 v[58:59], v[22:23], v[56:57], v[58:59]
	v_lshlrev_b32_e32 v64, 16, v41
	v_and_b32_e32 v65, 0xffff0000, v41
	v_pk_mul_f32 v[44:45], v[44:45], v[54:55]
	v_lshlrev_b32_e32 v54, 16, v37
	v_pk_mul_f32 v[44:45], v[58:59], v[44:45]
	v_lshlrev_b32_e32 v58, 16, v39
	v_cvt_pk_bf16_f32 v34, v44, v45
	v_lshlrev_b32_e32 v44, 16, v35
	v_and_b32_e32 v45, 0xffff0000, v35
	v_and_b32_e32 v59, 0xffff0000, v39
	v_pk_fma_f32 v[44:45], v[4:5], v[44:45], v[28:29]
	v_and_b32_e32 v39, 0xffff0000, v51
	v_pk_fma_f32 v[44:45], v[12:13], v[58:59], v[44:45]
	v_and_b32_e32 v55, 0xffff0000, v37
	v_pk_fma_f32 v[44:45], v[20:21], v[38:39], v[44:45]
	v_lshlrev_b32_e32 v40, 16, v53
	v_pk_mul_f32 v[50:51], v[44:45], v[44:45]
	v_and_b32_e32 v41, 0xffff0000, v53
	v_fmamk_f32 v35, v50, 0xbdd2d3e8, v178
	v_mul_f32_e32 v35, v44, v35
	v_exp_f32_e32 v35, v35
	v_pk_fma_f32 v[52:53], v[8:9], v[54:55], v[32:33]
	s_mov_b32 s8, 0x13e00000
	v_pk_fma_f32 v[52:53], v[16:17], v[64:65], v[52:53]
	v_add_f32_e32 v35, 1.0, v35
	v_rcp_f32_e32 v36, v35
	v_fmamk_f32 v35, v51, 0xbdd2d3e8, v178
	v_mul_f32_e32 v35, v45, v35
	v_exp_f32_e32 v35, v35
	v_pk_fma_f32 v[52:53], v[24:25], v[40:41], v[52:53]
	v_pk_fma_f32 v[48:49], v[2:3], v[48:49], v[26:27]
	v_pk_fma_f32 v[60:61], v[6:7], v[60:61], v[30:31]
	v_add_f32_e32 v35, 1.0, v35
	v_rcp_f32_e32 v37, v35
	v_pk_fma_f32 v[48:49], v[10:11], v[46:47], v[48:49]
	v_pk_fma_f32 v[60:61], v[14:15], v[56:57], v[60:61]
	v_pk_fma_f32 v[64:65], v[8:9], v[64:65], v[32:33]
	v_pk_mul_f32 v[36:37], v[44:45], v[36:37]
	v_lshl_add_u64 v[44:45], v[42:43], 0, s[2:3]
	v_pk_mul_f32 v[36:37], v[52:53], v[36:37]
	v_pk_fma_f32 v[64:65], v[16:17], v[40:41], v[64:65]
	v_cvt_pk_bf16_f32 v35, v36, v37
	v_add_co_u32_e32 v36, vcc, s8, v44
	s_mov_b32 s8, 0x13e01000
	s_nop 0
	v_addc_co_u32_e32 v37, vcc, 0, v45, vcc
	global_store_dwordx2 v[36:37], v[34:35], off nt
	ds_read2_b64 v[34:37], v62 offset0:66 offset1:98
	v_pk_fma_f32 v[46:47], v[2:3], v[46:47], v[26:27]
	v_pk_fma_f32 v[56:57], v[6:7], v[56:57], v[30:31]
	v_pk_fma_f32 v[40:41], v[8:9], v[40:41], v[32:33]
	s_add_u32 s2, s2, 0x5800
	s_waitcnt lgkmcnt(0)
	v_lshlrev_b32_e32 v54, 16, v34
	v_and_b32_e32 v55, 0xffff0000, v34
	v_pk_fma_f32 v[48:49], v[18:19], v[54:55], v[48:49]
	v_lshlrev_b32_e32 v52, 16, v36
	v_pk_mul_f32 v[50:51], v[48:49], v[48:49]
	v_and_b32_e32 v53, 0xffff0000, v36
	v_fmamk_f32 v34, v50, 0xbdd2d3e8, v178
	v_mul_f32_e32 v34, v48, v34
	v_exp_f32_e32 v34, v34
	v_pk_fma_f32 v[60:61], v[22:23], v[52:53], v[60:61]
	v_pk_fma_f32 v[46:47], v[10:11], v[54:55], v[46:47]
	v_pk_fma_f32 v[56:57], v[14:15], v[52:53], v[56:57]
	v_add_f32_e32 v34, 1.0, v34
	v_rcp_f32_e32 v50, v34
	v_fmamk_f32 v34, v51, 0xbdd2d3e8, v178
	v_mul_f32_e32 v34, v49, v34
	v_exp_f32_e32 v34, v34
	v_pk_fma_f32 v[54:55], v[2:3], v[54:55], v[26:27]
	v_pk_fma_f32 v[52:53], v[6:7], v[52:53], v[30:31]
	s_addc_u32 s3, s3, 0
	v_add_f32_e32 v34, 1.0, v34
	v_rcp_f32_e32 v51, v34
	s_cmp_eq_u32 s2, 0x16000
	v_pk_mul_f32 v[48:49], v[48:49], v[50:51]
	s_nop 0
	v_pk_mul_f32 v[48:49], v[60:61], v[48:49]
	v_lshlrev_b32_e32 v50, 16, v35
	v_cvt_pk_bf16_f32 v34, v48, v49
	v_pk_fma_f32 v[48:49], v[4:5], v[58:59], v[28:29]
	v_and_b32_e32 v51, 0xffff0000, v35
	v_pk_fma_f32 v[48:49], v[12:13], v[38:39], v[48:49]
	v_pk_fma_f32 v[38:39], v[4:5], v[38:39], v[28:29]
	v_pk_fma_f32 v[58:59], v[20:21], v[50:51], v[48:49]
	v_lshlrev_b32_e32 v48, 16, v37
	v_pk_mul_f32 v[60:61], v[58:59], v[58:59]
	v_and_b32_e32 v49, 0xffff0000, v37
	v_fmamk_f32 v35, v60, 0xbdd2d3e8, v178
	v_mul_f32_e32 v35, v58, v35
	v_exp_f32_e32 v35, v35
	v_pk_fma_f32 v[64:65], v[24:25], v[48:49], v[64:65]
	v_pk_fma_f32 v[38:39], v[12:13], v[50:51], v[38:39]
	v_pk_fma_f32 v[40:41], v[16:17], v[48:49], v[40:41]
	v_add_f32_e32 v35, 1.0, v35
	v_rcp_f32_e32 v36, v35
	v_fmamk_f32 v35, v61, 0xbdd2d3e8, v178
	v_mul_f32_e32 v35, v59, v35
	v_exp_f32_e32 v35, v35
	v_pk_fma_f32 v[50:51], v[4:5], v[50:51], v[28:29]
	v_pk_fma_f32 v[48:49], v[8:9], v[48:49], v[32:33]
	v_add_f32_e32 v35, 1.0, v35
	v_rcp_f32_e32 v37, v35
	s_nop 0
	v_pk_mul_f32 v[36:37], v[58:59], v[36:37]
	s_nop 0
	v_pk_mul_f32 v[36:37], v[64:65], v[36:37]
	s_nop 0
	v_cvt_pk_bf16_f32 v35, v36, v37
	v_add_co_u32_e32 v36, vcc, s8, v44
	s_mov_b32 s8, 0x13e02000
	s_nop 0
	v_addc_co_u32_e32 v37, vcc, 0, v45, vcc
	global_store_dwordx2 v[36:37], v[34:35], off offset:1536 nt
	ds_read2_b64 v[34:37], v62 offset0:132 offset1:164
	s_waitcnt lgkmcnt(0)
	v_lshlrev_b32_e32 v60, 16, v34
	v_and_b32_e32 v61, 0xffff0000, v34
	v_pk_fma_f32 v[46:47], v[18:19], v[60:61], v[46:47]
	v_and_b32_e32 v59, 0xffff0000, v36
	v_pk_mul_f32 v[64:65], v[46:47], v[46:47]
	v_pk_fma_f32 v[54:55], v[10:11], v[60:61], v[54:55]
	v_fmamk_f32 v58, v64, 0xbdd2d3e8, v178
	v_fmamk_f32 v63, v65, 0xbdd2d3e8, v178
	v_mul_f32_e32 v58, v46, v58
	v_mul_f32_e32 v63, v47, v63
	v_exp_f32_e32 v58, v58
	v_exp_f32_e32 v63, v63
	v_add_f32_e32 v58, 1.0, v58
	v_add_f32_e32 v63, 1.0, v63
	v_rcp_f32_e32 v64, v58
	v_rcp_f32_e32 v65, v63
	v_lshlrev_b32_e32 v58, 16, v36
	v_pk_fma_f32 v[56:57], v[22:23], v[58:59], v[56:57]
	v_pk_fma_f32 v[52:53], v[14:15], v[58:59], v[52:53]
	v_pk_mul_f32 v[46:47], v[46:47], v[64:65]
	s_nop 0
	v_pk_mul_f32 v[46:47], v[56:57], v[46:47]
	v_lshlrev_b32_e32 v56, 16, v35
	v_and_b32_e32 v57, 0xffff0000, v35
	v_pk_fma_f32 v[38:39], v[20:21], v[56:57], v[38:39]
	v_cvt_pk_bf16_f32 v64, v46, v47
	v_pk_mul_f32 v[66:67], v[38:39], v[38:39]
	v_and_b32_e32 v47, 0xffff0000, v37
	v_fmamk_f32 v46, v66, 0xbdd2d3e8, v178
	v_fmamk_f32 v63, v67, 0xbdd2d3e8, v178
	v_mul_f32_e32 v46, v38, v46
	v_mul_f32_e32 v63, v39, v63
	v_exp_f32_e32 v46, v46
	v_exp_f32_e32 v63, v63
	v_pk_fma_f32 v[50:51], v[12:13], v[56:57], v[50:51]
	v_add_f32_e32 v46, 1.0, v46
	v_add_f32_e32 v63, 1.0, v63
	v_rcp_f32_e32 v66, v46
	v_rcp_f32_e32 v67, v63
	v_lshlrev_b32_e32 v46, 16, v37
	v_pk_fma_f32 v[40:41], v[24:25], v[46:47], v[40:41]
	v_pk_fma_f32 v[46:47], v[16:17], v[46:47], v[48:49]
	v_pk_mul_f32 v[38:39], v[38:39], v[66:67]
	s_nop 0
	v_pk_mul_f32 v[38:39], v[40:41], v[38:39]
	s_nop 0
	v_cvt_pk_bf16_f32 v65, v38, v39
	v_add_co_u32_e32 v38, vcc, s8, v44
	s_nop 1
	v_addc_co_u32_e32 v39, vcc, 0, v45, vcc
	global_store_dwordx2 v[38:39], v[64:65], off offset:3072 nt
	ds_read2_b64 v[38:41], v62 offset0:198 offset1:230
	v_add_co_u32_e32 v44, vcc, s37, v44
	v_add_u32_e32 v62, 0x840, v62
	s_nop 0
	v_addc_co_u32_e32 v45, vcc, 0, v45, vcc
	s_waitcnt lgkmcnt(0)
	v_lshlrev_b32_e32 v64, 16, v38
	v_and_b32_e32 v65, 0xffff0000, v38
	v_pk_fma_f32 v[54:55], v[18:19], v[64:65], v[54:55]
	v_lshlrev_b32_e32 v64, 16, v40
	v_pk_mul_f32 v[60:61], v[54:55], v[54:55]
	v_and_b32_e32 v65, 0xffff0000, v40
	v_fmamk_f32 v60, v60, 0xbdd2d3e8, v178
	v_fmamk_f32 v58, v61, 0xbdd2d3e8, v178
	v_mul_f32_e32 v60, v54, v60
	v_mul_f32_e32 v58, v55, v58
	v_exp_f32_e32 v60, v60
	v_exp_f32_e32 v58, v58
	v_pk_fma_f32 v[52:53], v[22:23], v[64:65], v[52:53]
	v_lshlrev_b32_e32 v56, 16, v41
	v_add_f32_e32 v60, 1.0, v60
	v_add_f32_e32 v58, 1.0, v58
	v_rcp_f32_e32 v60, v60
	v_rcp_f32_e32 v61, v58
	v_and_b32_e32 v57, 0xffff0000, v41
	v_pk_fma_f32 v[46:47], v[24:25], v[56:57], v[46:47]
	v_pk_mul_f32 v[54:55], v[54:55], v[60:61]
	s_nop 0
	v_pk_mul_f32 v[52:53], v[52:53], v[54:55]
	v_lshlrev_b32_e32 v54, 16, v39
	v_and_b32_e32 v55, 0xffff0000, v39
	v_pk_fma_f32 v[50:51], v[20:21], v[54:55], v[50:51]
	v_cvt_pk_bf16_f32 v52, v52, v53
	v_pk_mul_f32 v[54:55], v[50:51], v[50:51]
	s_nop 0
	v_fmamk_f32 v53, v54, 0xbdd2d3e8, v178
	v_fmamk_f32 v48, v55, 0xbdd2d3e8, v178
	v_mul_f32_e32 v53, v50, v53
	v_mul_f32_e32 v48, v51, v48
	v_exp_f32_e32 v53, v53
	v_exp_f32_e32 v48, v48
	v_add_f32_e32 v53, 1.0, v53
	v_add_f32_e32 v48, 1.0, v48
	v_rcp_f32_e32 v54, v53
	v_rcp_f32_e32 v55, v48
	s_nop 0
	v_pk_mul_f32 v[48:49], v[50:51], v[54:55]
	s_nop 0
	v_pk_mul_f32 v[46:47], v[46:47], v[48:49]
	s_nop 0
	v_cvt_pk_bf16_f32 v53, v46, v47
	global_store_dwordx2 v[44:45], v[52:53], off offset:512 nt
	s_cbranch_scc0 .LBB0_42
	s_add_i32 s16, s99, s16
	s_cmpk_gt_i32 s16, 0xaff
	s_cbranch_scc0 .LBB0_32
